# v9 + nontemporal loads and stores in the final post-norm phase (P14)
# speedup vs baseline: 1.0034x; 1.0034x over previous
.LBB0_2057:
	s_or_b64 exec, exec, s[0:1]
	s_waitcnt lgkmcnt(0)
	s_and_b64 vcc, exec, s[4:5]
	s_waitcnt lgkmcnt(0)
	s_barrier
	s_cbranch_vccnz .LBB0_2066
	s_add_u32 s0, s2, 0x1f600000
	s_addc_u32 s1, s3, 0
	s_add_u32 s2, s2, 0x27800000
	s_addc_u32 s3, s3, 0
	s_ashr_i32 s25, s24, 31
	s_lshl_b64 s[4:5], s[24:25], 13
	s_add_u32 s6, s2, s4
	v_ashrrev_i32_e32 v71, 31, v70
	s_addc_u32 s7, s3, s5
	v_lshlrev_b64 v[34:35], 3, v[70:71]
	v_lshl_add_u64 v[16:17], s[6:7], 0, v[34:35]
	s_movk_i32 s6, 0x1000
	v_add_co_u32_e32 v32, vcc, s6, v16
	s_add_u32 s4, s0, s4
	s_nop 0
	v_addc_co_u32_e32 v33, vcc, 0, v17, vcc
	s_addc_u32 s5, s1, s5
	global_load_dwordx2 v[0:1], v[16:17], off nt
	global_load_dwordx2 v[2:3], v[16:17], off offset:512 nt
	global_load_dwordx2 v[4:5], v[16:17], off offset:1024 nt
	global_load_dwordx2 v[6:7], v[16:17], off offset:1536 nt
	global_load_dwordx2 v[8:9], v[16:17], off offset:2048 nt
	global_load_dwordx2 v[10:11], v[16:17], off offset:2560 nt
	global_load_dwordx2 v[12:13], v[16:17], off offset:3072 nt
	global_load_dwordx2 v[14:15], v[16:17], off offset:3584 nt
	s_nop 0
	global_load_dwordx2 v[16:17], v[32:33], off nt
	global_load_dwordx2 v[18:19], v[32:33], off offset:512 nt
	global_load_dwordx2 v[20:21], v[32:33], off offset:1024 nt
	global_load_dwordx2 v[22:23], v[32:33], off offset:1536 nt
	global_load_dwordx2 v[24:25], v[32:33], off offset:2048 nt
	global_load_dwordx2 v[26:27], v[32:33], off offset:2560 nt
	global_load_dwordx2 v[28:29], v[32:33], off offset:3072 nt
	global_load_dwordx2 v[30:31], v[32:33], off offset:3584 nt
	v_lshl_add_u64 v[32:33], s[4:5], 0, v[34:35]
	global_load_dwordx2 v[38:39], v[32:33], off nt
	global_load_dwordx2 v[40:41], v[32:33], off offset:512 nt
	global_load_dwordx2 v[42:43], v[32:33], off offset:1024 nt
	global_load_dwordx2 v[44:45], v[32:33], off offset:1536 nt
	global_load_dwordx2 v[46:47], v[32:33], off offset:2048 nt
	global_load_dwordx2 v[48:49], v[32:33], off offset:2560 nt
	global_load_dwordx2 v[50:51], v[32:33], off offset:3072 nt
	global_load_dwordx2 v[52:53], v[32:33], off offset:3584 nt
	v_add_co_u32_e32 v32, vcc, s6, v32
	v_mov_b32_e32 v36, s10
	s_nop 0
	v_addc_co_u32_e32 v33, vcc, 0, v33, vcc
	global_load_dwordx2 v[54:55], v[32:33], off nt
	global_load_dwordx2 v[56:57], v[32:33], off offset:512 nt
	global_load_dwordx2 v[58:59], v[32:33], off offset:1024 nt
	global_load_dwordx2 v[60:61], v[32:33], off offset:1536 nt
	global_load_dwordx2 v[62:63], v[32:33], off offset:2048 nt
	global_load_dwordx2 v[64:65], v[32:33], off offset:2560 nt
	global_load_dwordx2 v[66:67], v[32:33], off offset:3072 nt
	global_load_dwordx2 v[68:69], v[32:33], off offset:3584 nt
	v_mov_b32_e32 v37, s11
	v_lshl_add_u64 v[32:33], s[2:3], 0, v[34:35]
	v_lshl_add_u64 v[34:35], s[0:1], 0, v[34:35]
	v_lshl_add_u64 v[36:37], v[70:71], 4, v[36:37]
	v_lshl_add_u32 v151, v70, 4, 0
	s_lshl_b32 s7, s72, 4
	v_mov_b32_e32 v198, 0x358637bd
	s_mov_b32 s8, 0xf800000
	v_mov_b32_e32 v199, 0x260
	s_movk_i32 s9, 0x2000
	s_movk_i32 s10, 0x3000
	s_branch .LBB0_2061
.LBB0_2059:
	v_and_b32_e32 v211, 0xffff0000, v70
	v_and_b32_e32 v213, 0xffff0000, v71
	v_lshlrev_b32_e32 v210, 16, v70
	v_lshlrev_b32_e32 v212, 16, v71
	v_mul_f32_e32 v134, v211, v211
	v_mul_f32_e32 v135, v213, v213
	v_fmac_f32_e32 v134, v210, v210
	v_fmac_f32_e32 v135, v212, v212
	v_and_b32_e32 v197, 0xffff0000, v72
	v_and_b32_e32 v195, 0xffff0000, v73
	v_add_f32_e32 v134, v134, v135
	v_lshlrev_b32_e32 v196, 16, v72
	v_lshlrev_b32_e32 v194, 16, v73
	v_mul_f32_e32 v135, v197, v197
	v_mul_f32_e32 v136, v195, v195
	v_fmac_f32_e32 v135, v196, v196
	v_fmac_f32_e32 v136, v194, v194
	v_add_f32_e32 v135, v135, v136
	v_and_b32_e32 v193, 0xffff0000, v74
	v_and_b32_e32 v191, 0xffff0000, v75
	v_add_f32_e32 v134, v135, v134
	v_lshlrev_b32_e32 v192, 16, v74
	v_lshlrev_b32_e32 v190, 16, v75
	v_mul_f32_e32 v135, v193, v193
	v_mul_f32_e32 v136, v191, v191
	v_fmac_f32_e32 v135, v192, v192
	v_fmac_f32_e32 v136, v190, v190
	v_add_f32_e32 v135, v135, v136
	v_and_b32_e32 v189, 0xffff0000, v76
	v_and_b32_e32 v187, 0xffff0000, v77
	v_add_f32_e32 v134, v135, v134
	v_lshlrev_b32_e32 v188, 16, v76
	v_lshlrev_b32_e32 v186, 16, v77
	v_mul_f32_e32 v135, v189, v189
	v_mul_f32_e32 v136, v187, v187
	v_fmac_f32_e32 v135, v188, v188
	v_fmac_f32_e32 v136, v186, v186
	v_add_f32_e32 v135, v135, v136
	v_and_b32_e32 v185, 0xffff0000, v80
	v_and_b32_e32 v183, 0xffff0000, v81
	v_add_f32_e32 v134, v135, v134
	v_lshlrev_b32_e32 v184, 16, v80
	v_lshlrev_b32_e32 v182, 16, v81
	v_mul_f32_e32 v135, v185, v185
	v_mul_f32_e32 v136, v183, v183
	v_fmac_f32_e32 v135, v184, v184
	v_fmac_f32_e32 v136, v182, v182
	v_add_f32_e32 v135, v135, v136
	v_and_b32_e32 v181, 0xffff0000, v84
	v_and_b32_e32 v179, 0xffff0000, v85
	v_add_f32_e32 v134, v135, v134
	v_lshlrev_b32_e32 v180, 16, v84
	v_lshlrev_b32_e32 v178, 16, v85
	v_mul_f32_e32 v135, v181, v181
	v_mul_f32_e32 v136, v179, v179
	v_fmac_f32_e32 v135, v180, v180
	v_fmac_f32_e32 v136, v178, v178
	v_add_f32_e32 v135, v135, v136
	v_and_b32_e32 v177, 0xffff0000, v88
	v_and_b32_e32 v175, 0xffff0000, v89
	v_add_f32_e32 v134, v135, v134
	v_lshlrev_b32_e32 v176, 16, v88
	v_lshlrev_b32_e32 v174, 16, v89
	v_mul_f32_e32 v135, v177, v177
	v_mul_f32_e32 v136, v175, v175
	v_fmac_f32_e32 v135, v176, v176
	v_fmac_f32_e32 v136, v174, v174
	v_add_f32_e32 v135, v135, v136
	v_and_b32_e32 v171, 0xffff0000, v92
	v_and_b32_e32 v169, 0xffff0000, v93
	v_add_f32_e32 v134, v135, v134
	v_lshlrev_b32_e32 v170, 16, v92
	v_lshlrev_b32_e32 v168, 16, v93
	v_mul_f32_e32 v135, v171, v171
	v_mul_f32_e32 v136, v169, v169
	v_fmac_f32_e32 v135, v170, v170
	v_fmac_f32_e32 v136, v168, v168
	v_add_f32_e32 v135, v135, v136
	v_and_b32_e32 v167, 0xffff0000, v100
	v_and_b32_e32 v165, 0xffff0000, v101
	v_add_f32_e32 v134, v135, v134
	v_lshlrev_b32_e32 v166, 16, v100
	v_lshlrev_b32_e32 v164, 16, v101
	v_mul_f32_e32 v135, v167, v167
	v_mul_f32_e32 v136, v165, v165
	v_fmac_f32_e32 v135, v166, v166
	v_fmac_f32_e32 v136, v164, v164
	v_add_f32_e32 v135, v135, v136
	v_and_b32_e32 v161, 0xffff0000, v104
	v_and_b32_e32 v163, 0xffff0000, v105
	v_add_f32_e32 v134, v135, v134
	v_lshlrev_b32_e32 v160, 16, v104
	v_lshlrev_b32_e32 v162, 16, v105
	v_mul_f32_e32 v135, v161, v161
	v_mul_f32_e32 v136, v163, v163
	v_fmac_f32_e32 v135, v160, v160
	v_fmac_f32_e32 v136, v162, v162
	v_add_f32_e32 v135, v135, v136
	v_and_b32_e32 v157, 0xffff0000, v106
	v_and_b32_e32 v159, 0xffff0000, v107
	v_add_f32_e32 v134, v135, v134
	v_lshlrev_b32_e32 v156, 16, v106
	v_lshlrev_b32_e32 v158, 16, v107
	v_mul_f32_e32 v135, v157, v157
	v_mul_f32_e32 v136, v159, v159
	v_fmac_f32_e32 v135, v156, v156
	v_fmac_f32_e32 v136, v158, v158
	v_add_f32_e32 v135, v135, v136
	v_and_b32_e32 v153, 0xffff0000, v108
	v_and_b32_e32 v155, 0xffff0000, v109
	v_add_f32_e32 v134, v135, v134
	v_lshlrev_b32_e32 v152, 16, v108
	v_lshlrev_b32_e32 v154, 16, v109
	v_mul_f32_e32 v135, v153, v153
	v_mul_f32_e32 v136, v155, v155
	v_fmac_f32_e32 v135, v152, v152
	v_fmac_f32_e32 v136, v154, v154
	v_add_f32_e32 v135, v135, v136
	v_and_b32_e32 v147, 0xffff0000, v112
	v_and_b32_e32 v149, 0xffff0000, v113
	v_add_f32_e32 v134, v135, v134
	v_lshlrev_b32_e32 v146, 16, v112
	v_lshlrev_b32_e32 v148, 16, v113
	v_mul_f32_e32 v135, v147, v147
	v_mul_f32_e32 v136, v149, v149
	v_fmac_f32_e32 v135, v146, v146
	v_fmac_f32_e32 v136, v148, v148
	v_add_f32_e32 v135, v135, v136
	v_and_b32_e32 v143, 0xffff0000, v116
	v_and_b32_e32 v145, 0xffff0000, v117
	v_add_f32_e32 v134, v135, v134
	v_lshlrev_b32_e32 v142, 16, v116
	v_lshlrev_b32_e32 v144, 16, v117
	v_mul_f32_e32 v135, v143, v143
	v_mul_f32_e32 v136, v145, v145
	v_fmac_f32_e32 v135, v142, v142
	v_fmac_f32_e32 v136, v144, v144
	v_add_f32_e32 v135, v135, v136
	v_and_b32_e32 v139, 0xffff0000, v120
	v_and_b32_e32 v141, 0xffff0000, v121
	v_add_f32_e32 v134, v135, v134
	v_lshlrev_b32_e32 v138, 16, v120
	v_lshlrev_b32_e32 v140, 16, v121
	v_mul_f32_e32 v135, v139, v139
	v_mul_f32_e32 v136, v141, v141
	v_fmac_f32_e32 v135, v138, v138
	v_fmac_f32_e32 v136, v140, v140
	v_add_f32_e32 v135, v135, v136
	v_add_f32_e32 v150, v135, v134
	v_and_b32_e32 v135, 0xffff0000, v124
	v_and_b32_e32 v137, 0xffff0000, v125
	v_lshlrev_b32_e32 v134, 16, v124
	v_lshlrev_b32_e32 v136, 16, v125
	v_mul_f32_e32 v172, v135, v135
	v_mul_f32_e32 v173, v137, v137
	v_fmac_f32_e32 v172, v134, v134
	v_fmac_f32_e32 v173, v136, v136
	v_add_f32_e32 v172, v172, v173
	v_add_f32_e32 v150, v172, v150
	ds_bpermute_b32 v172, v204, v150
	s_ashr_i32 s3, s2, 31
	v_lshlrev_b32_e32 v214, 16, v78
	v_and_b32_e32 v215, 0xffff0000, v78
	s_waitcnt lgkmcnt(0)
	v_add_f32_e32 v150, v150, v172
	ds_bpermute_b32 v172, v205, v150
	v_lshlrev_b32_e32 v216, 16, v79
	v_and_b32_e32 v217, 0xffff0000, v79
	s_add_i32 s4, s2, s33
	s_waitcnt lgkmcnt(0)
	v_add_f32_e32 v150, v150, v172
	ds_bpermute_b32 v172, v206, v150
	s_waitcnt lgkmcnt(0)
	v_add_f32_e32 v150, v150, v172
	ds_bpermute_b32 v172, v207, v150
	s_waitcnt lgkmcnt(0)
	v_add_f32_e32 v150, v150, v172
	ds_bpermute_b32 v172, v208, v150
	s_waitcnt lgkmcnt(0)
	v_add_f32_e32 v150, v150, v172
	ds_bpermute_b32 v172, v209, v150
	s_waitcnt lgkmcnt(0)
	v_add_f32_e32 v150, v150, v172
	v_fmamk_f32 v150, v150, 0x39800000, v198
	v_mul_f32_e32 v172, 0x4f800000, v150
	v_cmp_gt_f32_e32 vcc, s8, v150
	s_nop 1
	v_cndmask_b32_e32 v150, v150, v172, vcc
	v_sqrt_f32_e32 v172, v150
	s_nop 0
	v_add_u32_e32 v173, -1, v172
	v_fma_f32 v200, -v173, v172, v150
	v_cmp_ge_f32_e64 s[0:1], 0, v200
	v_add_u32_e32 v200, 1, v172
	s_nop 0
	v_cndmask_b32_e64 v173, v172, v173, s[0:1]
	v_fma_f32 v172, -v200, v172, v150
	v_cmp_lt_f32_e64 s[0:1], 0, v172
	s_nop 1
	v_cndmask_b32_e64 v172, v173, v200, s[0:1]
	v_mul_f32_e32 v173, 0x37800000, v172
	v_cndmask_b32_e32 v172, v172, v173, vcc
	v_cmp_class_f32_e32 vcc, v150, v199
	s_nop 1
	v_cndmask_b32_e32 v150, v172, v150, vcc
	v_div_scale_f32 v172, s[0:1], v150, v150, 1.0
	v_rcp_f32_e32 v173, v172
	s_lshl_b64 s[0:1], s[2:3], 14
	s_cmpk_gt_i32 s4, 0x3fff
	v_fma_f32 v200, -v172, v173, 1.0
	v_fmac_f32_e32 v173, v200, v173
	v_div_scale_f32 v200, vcc, 1.0, v150, 1.0
	v_mul_f32_e32 v201, v200, v173
	v_fma_f32 v202, -v172, v201, v200
	v_fmac_f32_e32 v201, v202, v173
	v_fma_f32 v172, -v172, v201, v200
	v_div_fmas_f32 v172, v172, v173, v201
	v_div_fixup_f32 v150, v172, v150, 1.0
	ds_read_b128 v[200:203], v151
	v_mul_f32_e32 v150, 0.5, v150
	v_pk_mul_f32 v[218:219], v[150:151], v[210:211] op_sel_hi:[0,1]
	v_pk_mul_f32 v[220:221], v[150:151], v[212:213] op_sel_hi:[0,1]
	ds_read_b128 v[210:213], v151 offset:1024
	v_lshl_add_u64 v[172:173], v[36:37], 0, s[0:1]
	s_waitcnt lgkmcnt(1)
	v_pk_fma_f32 v[202:203], v[202:203], v[220:221], v[216:217]
	v_pk_fma_f32 v[200:201], v[200:201], v[218:219], v[214:215]
	global_store_dwordx4 v[172:173], v[200:203], off nt
	v_pk_mul_f32 v[214:215], v[150:151], v[196:197] op_sel_hi:[0,1]
	v_pk_mul_f32 v[194:195], v[150:151], v[194:195] op_sel_hi:[0,1]
	v_lshlrev_b32_e32 v200, 16, v82
	v_and_b32_e32 v201, 0xffff0000, v82
	v_lshlrev_b32_e32 v202, 16, v83
	v_and_b32_e32 v203, 0xffff0000, v83
	s_waitcnt lgkmcnt(0)
	v_pk_fma_f32 v[196:197], v[212:213], v[194:195], v[202:203]
	v_pk_fma_f32 v[194:195], v[210:211], v[214:215], v[200:201]
	global_store_dwordx4 v[172:173], v[194:197], off offset:1024 nt
	ds_read_b128 v[194:197], v151 offset:2048
	v_pk_mul_f32 v[210:211], v[150:151], v[192:193] op_sel_hi:[0,1]
	v_pk_mul_f32 v[212:213], v[150:151], v[190:191] op_sel_hi:[0,1]
	ds_read_b128 v[190:193], v151 offset:3072
	v_lshlrev_b32_e32 v200, 16, v86
	v_and_b32_e32 v201, 0xffff0000, v86
	v_lshlrev_b32_e32 v202, 16, v87
	v_and_b32_e32 v203, 0xffff0000, v87
	s_waitcnt lgkmcnt(1)
	v_pk_fma_f32 v[196:197], v[196:197], v[212:213], v[202:203]
	v_pk_fma_f32 v[194:195], v[194:195], v[210:211], v[200:201]
	global_store_dwordx4 v[172:173], v[194:197], off offset:2048 nt
	v_pk_mul_f32 v[200:201], v[150:151], v[188:189] op_sel_hi:[0,1]
	v_pk_mul_f32 v[186:187], v[150:151], v[186:187] op_sel_hi:[0,1]
	v_lshlrev_b32_e32 v194, 16, v90
	v_and_b32_e32 v195, 0xffff0000, v90
	v_lshlrev_b32_e32 v196, 16, v91
	v_and_b32_e32 v197, 0xffff0000, v91
	s_waitcnt lgkmcnt(0)
	v_pk_fma_f32 v[188:189], v[192:193], v[186:187], v[196:197]
	v_pk_fma_f32 v[186:187], v[190:191], v[200:201], v[194:195]
	global_store_dwordx4 v[172:173], v[186:189], off offset:3072 nt
	ds_read_b128 v[186:189], v151 offset:4096
	v_lshlrev_b32_e32 v190, 16, v94
	v_and_b32_e32 v191, 0xffff0000, v94
	v_pk_mul_f32 v[194:195], v[150:151], v[184:185] op_sel_hi:[0,1]
	v_pk_mul_f32 v[196:197], v[150:151], v[182:183] op_sel_hi:[0,1]
	ds_read_b128 v[182:185], v151 offset:5120
	s_waitcnt lgkmcnt(1)
	v_pk_fma_f32 v[186:187], v[186:187], v[194:195], v[190:191]
	v_add_co_u32_e32 v190, vcc, s6, v172
	v_lshlrev_b32_e32 v192, 16, v95
	v_and_b32_e32 v193, 0xffff0000, v95
	v_addc_co_u32_e32 v191, vcc, 0, v173, vcc
	v_pk_fma_f32 v[188:189], v[188:189], v[196:197], v[192:193]
	v_add_co_u32_e32 v192, vcc, s9, v172
	v_pk_mul_f32 v[194:195], v[150:151], v[180:181] op_sel_hi:[0,1]
	s_nop 0
	v_addc_co_u32_e32 v193, vcc, 0, v173, vcc
	global_store_dwordx4 v[192:193], v[186:189], off offset:-4096 nt
	v_pk_mul_f32 v[178:179], v[150:151], v[178:179] op_sel_hi:[0,1]
	v_pk_mul_f32 v[168:169], v[150:151], v[168:169] op_sel_hi:[0,1]
	v_lshlrev_b32_e32 v186, 16, v96
	v_and_b32_e32 v187, 0xffff0000, v96
	v_lshlrev_b32_e32 v188, 16, v97
	v_and_b32_e32 v189, 0xffff0000, v97
	s_waitcnt lgkmcnt(0)
	v_pk_fma_f32 v[180:181], v[178:179], v[184:185], v[188:189]
	v_pk_fma_f32 v[178:179], v[194:195], v[182:183], v[186:187]
	global_store_dwordx4 v[190:191], v[178:181], off offset:1024 nt
	ds_read_b128 v[178:181], v151 offset:6144
	v_pk_mul_f32 v[186:187], v[150:151], v[176:177] op_sel_hi:[0,1]
	v_pk_mul_f32 v[188:189], v[150:151], v[174:175] op_sel_hi:[0,1]
	ds_read_b128 v[174:177], v151 offset:7168
	v_lshlrev_b32_e32 v182, 16, v98
	v_and_b32_e32 v183, 0xffff0000, v98
	v_lshlrev_b32_e32 v184, 16, v99
	v_and_b32_e32 v185, 0xffff0000, v99
	s_waitcnt lgkmcnt(1)
	v_pk_fma_f32 v[180:181], v[188:189], v[180:181], v[184:185]
	v_pk_fma_f32 v[178:179], v[186:187], v[178:179], v[182:183]
	global_store_dwordx4 v[190:191], v[178:181], off offset:2048 nt
	v_pk_mul_f32 v[182:183], v[150:151], v[170:171] op_sel_hi:[0,1]
	v_pk_mul_f32 v[162:163], v[150:151], v[162:163] op_sel_hi:[0,1]
	v_lshlrev_b32_e32 v178, 16, v102
	v_and_b32_e32 v179, 0xffff0000, v102
	v_lshlrev_b32_e32 v180, 16, v103
	v_and_b32_e32 v181, 0xffff0000, v103
	s_waitcnt lgkmcnt(0)
	v_pk_fma_f32 v[170:171], v[168:169], v[176:177], v[180:181]
	v_pk_fma_f32 v[168:169], v[182:183], v[174:175], v[178:179]
	global_store_dwordx4 v[190:191], v[168:171], off offset:3072 nt
	ds_read_b128 v[168:171], v151 offset:8192
	v_pk_mul_f32 v[178:179], v[150:151], v[166:167] op_sel_hi:[0,1]
	v_pk_mul_f32 v[180:181], v[150:151], v[164:165] op_sel_hi:[0,1]
	ds_read_b128 v[164:167], v151 offset:9216
	v_lshlrev_b32_e32 v174, 16, v110
	v_and_b32_e32 v175, 0xffff0000, v110
	v_lshlrev_b32_e32 v176, 16, v111
	v_and_b32_e32 v177, 0xffff0000, v111
	s_waitcnt lgkmcnt(1)
	v_pk_fma_f32 v[170:171], v[180:181], v[170:171], v[176:177]
	v_pk_fma_f32 v[168:169], v[178:179], v[168:169], v[174:175]
	global_store_dwordx4 v[192:193], v[168:171], off nt
	v_pk_mul_f32 v[160:161], v[150:151], v[160:161] op_sel_hi:[0,1]
	v_pk_mul_f32 v[154:155], v[150:151], v[154:155] op_sel_hi:[0,1]
	v_lshlrev_b32_e32 v168, 16, v114
	v_and_b32_e32 v169, 0xffff0000, v114
	v_lshlrev_b32_e32 v170, 16, v115
	v_and_b32_e32 v171, 0xffff0000, v115
	s_waitcnt lgkmcnt(0)
	v_pk_fma_f32 v[160:161], v[160:161], v[164:165], v[168:169]
	v_pk_fma_f32 v[162:163], v[162:163], v[166:167], v[170:171]
	global_store_dwordx4 v[192:193], v[160:163], off offset:1024 nt
	ds_read_b128 v[160:163], v151 offset:10240
	v_pk_mul_f32 v[168:169], v[150:151], v[158:159] op_sel_hi:[0,1]
	v_pk_mul_f32 v[170:171], v[150:151], v[156:157] op_sel_hi:[0,1]
	ds_read_b128 v[156:159], v151 offset:11264
	v_lshlrev_b32_e32 v164, 16, v118
	v_and_b32_e32 v165, 0xffff0000, v118
	v_lshlrev_b32_e32 v166, 16, v119
	v_and_b32_e32 v167, 0xffff0000, v119
	s_waitcnt lgkmcnt(1)
	v_pk_fma_f32 v[160:161], v[170:171], v[160:161], v[164:165]
	v_pk_fma_f32 v[162:163], v[168:169], v[162:163], v[166:167]
	global_store_dwordx4 v[192:193], v[160:163], off offset:2048 nt
	v_pk_mul_f32 v[152:153], v[150:151], v[152:153] op_sel_hi:[0,1]
	v_pk_mul_f32 v[144:145], v[150:151], v[144:145] op_sel_hi:[0,1]
	v_lshlrev_b32_e32 v160, 16, v122
	v_and_b32_e32 v161, 0xffff0000, v122
	v_lshlrev_b32_e32 v162, 16, v123
	v_and_b32_e32 v163, 0xffff0000, v123
	s_waitcnt lgkmcnt(0)
	v_pk_fma_f32 v[152:153], v[152:153], v[156:157], v[160:161]
	v_pk_fma_f32 v[154:155], v[154:155], v[158:159], v[162:163]
	global_store_dwordx4 v[192:193], v[152:155], off offset:3072 nt
	ds_read_b128 v[152:155], v151 offset:12288
	v_pk_mul_f32 v[160:161], v[150:151], v[148:149] op_sel_hi:[0,1]
	v_pk_mul_f32 v[162:163], v[150:151], v[146:147] op_sel_hi:[0,1]
	ds_read_b128 v[146:149], v151 offset:13312
	v_lshlrev_b32_e32 v156, 16, v126
	v_and_b32_e32 v157, 0xffff0000, v126
	v_lshlrev_b32_e32 v158, 16, v127
	v_and_b32_e32 v159, 0xffff0000, v127
	s_waitcnt lgkmcnt(1)
	v_pk_fma_f32 v[152:153], v[162:163], v[152:153], v[156:157]
	v_add_co_u32_e32 v156, vcc, s10, v172
	v_pk_fma_f32 v[154:155], v[160:161], v[154:155], v[158:159]
	s_nop 0
	v_addc_co_u32_e32 v157, vcc, 0, v173, vcc
	global_store_dwordx4 v[156:157], v[152:155], off nt
	v_pk_mul_f32 v[142:143], v[150:151], v[142:143] op_sel_hi:[0,1]
	v_pk_mul_f32 v[136:137], v[150:151], v[136:137] op_sel_hi:[0,1]
	v_lshlrev_b32_e32 v152, 16, v128
	v_and_b32_e32 v153, 0xffff0000, v128
	v_lshlrev_b32_e32 v154, 16, v129
	v_and_b32_e32 v155, 0xffff0000, v129
	s_waitcnt lgkmcnt(0)
	v_pk_fma_f32 v[142:143], v[142:143], v[146:147], v[152:153]
	v_pk_fma_f32 v[144:145], v[144:145], v[148:149], v[154:155]
	global_store_dwordx4 v[156:157], v[142:145], off offset:1024 nt
	ds_read_b128 v[142:145], v151 offset:14336
	v_pk_mul_f32 v[152:153], v[150:151], v[140:141] op_sel_hi:[0,1]
	v_pk_mul_f32 v[154:155], v[150:151], v[138:139] op_sel_hi:[0,1]
	ds_read_b128 v[138:141], v151 offset:15360
	v_lshlrev_b32_e32 v146, 16, v130
	v_and_b32_e32 v147, 0xffff0000, v130
	v_lshlrev_b32_e32 v148, 16, v131
	v_and_b32_e32 v149, 0xffff0000, v131
	s_waitcnt lgkmcnt(1)
	v_pk_fma_f32 v[142:143], v[154:155], v[142:143], v[146:147]
	v_pk_fma_f32 v[144:145], v[152:153], v[144:145], v[148:149]
	global_store_dwordx4 v[156:157], v[142:145], off offset:2048 nt
	v_pk_mul_f32 v[134:135], v[150:151], v[134:135] op_sel_hi:[0,1]
	s_cselect_b64 s[0:1], -1, 0
	v_lshlrev_b32_e32 v142, 16, v132
	v_and_b32_e32 v143, 0xffff0000, v132
	v_lshlrev_b32_e32 v144, 16, v133
	v_and_b32_e32 v145, 0xffff0000, v133
	s_waitcnt lgkmcnt(0)
	v_pk_fma_f32 v[134:135], v[134:135], v[138:139], v[142:143]
	v_pk_fma_f32 v[136:137], v[136:137], v[140:141], v[144:145]
	global_store_dwordx4 v[156:157], v[134:137], off offset:3072 nt

.LBB0_2061:
	s_add_i32 s2, s24, s33
	s_cmpk_lt_i32 s2, 0x4000
	s_cselect_b64 s[4:5], -1, 0
	s_cmpk_gt_i32 s2, 0x3fff
	s_cbranch_scc1 .LBB0_2063
	s_ashr_i32 s3, s2, 31
	s_lshl_b64 s[0:1], s[2:3], 13
	v_lshl_add_u64 v[78:79], v[32:33], 0, s[0:1]
	global_load_dwordx2 v[70:71], v[78:79], off nt
	global_load_dwordx2 v[72:73], v[78:79], off offset:512 nt
	global_load_dwordx2 v[74:75], v[78:79], off offset:1024 nt
	global_load_dwordx2 v[76:77], v[78:79], off offset:1536 nt
	global_load_dwordx2 v[80:81], v[78:79], off offset:2048 nt
	global_load_dwordx2 v[84:85], v[78:79], off offset:2560 nt
	global_load_dwordx2 v[88:89], v[78:79], off offset:3072 nt
	global_load_dwordx2 v[92:93], v[78:79], off offset:3584 nt
	v_add_co_u32_e32 v78, vcc, 0x1000, v78
	v_lshl_add_u64 v[110:111], v[34:35], 0, s[0:1]
	s_nop 0
	v_addc_co_u32_e32 v79, vcc, 0, v79, vcc
	v_add_co_u32_e32 v132, vcc, 0x1000, v110
	global_load_dwordx2 v[100:101], v[78:79], off nt
	global_load_dwordx2 v[104:105], v[78:79], off offset:512 nt
	global_load_dwordx2 v[106:107], v[78:79], off offset:1024 nt
	global_load_dwordx2 v[108:109], v[78:79], off offset:1536 nt
	global_load_dwordx2 v[112:113], v[78:79], off offset:2048 nt
	global_load_dwordx2 v[116:117], v[78:79], off offset:2560 nt
	global_load_dwordx2 v[120:121], v[78:79], off offset:3072 nt
	global_load_dwordx2 v[124:125], v[78:79], off offset:3584 nt
	v_addc_co_u32_e32 v133, vcc, 0, v111, vcc
	global_load_dwordx2 v[78:79], v[110:111], off nt
	global_load_dwordx2 v[82:83], v[110:111], off offset:512 nt
	global_load_dwordx2 v[86:87], v[110:111], off offset:1024 nt
	global_load_dwordx2 v[90:91], v[110:111], off offset:1536 nt
	global_load_dwordx2 v[94:95], v[110:111], off offset:2048 nt
	global_load_dwordx2 v[96:97], v[110:111], off offset:2560 nt
	global_load_dwordx2 v[98:99], v[110:111], off offset:3072 nt
	global_load_dwordx2 v[102:103], v[110:111], off offset:3584 nt
	s_nop 0
	global_load_dwordx2 v[110:111], v[132:133], off nt
	global_load_dwordx2 v[114:115], v[132:133], off offset:512 nt
	global_load_dwordx2 v[118:119], v[132:133], off offset:1024 nt
	global_load_dwordx2 v[122:123], v[132:133], off offset:1536 nt
	global_load_dwordx2 v[126:127], v[132:133], off offset:2048 nt
	global_load_dwordx2 v[128:129], v[132:133], off offset:2560 nt
	global_load_dwordx2 v[130:131], v[132:133], off offset:3072 nt
	s_nop 0
	global_load_dwordx2 v[132:133], v[132:133], off offset:3584 nt
.LBB0_2063:
	s_waitcnt vmcnt(31)
	v_and_b32_e32 v211, 0xffff0000, v0
	v_and_b32_e32 v213, 0xffff0000, v1
	v_lshlrev_b32_e32 v210, 16, v0
	v_lshlrev_b32_e32 v212, 16, v1
	v_mul_f32_e32 v134, v211, v211
	v_mul_f32_e32 v135, v213, v213
	v_fmac_f32_e32 v134, v210, v210
	v_fmac_f32_e32 v135, v212, v212
	s_waitcnt vmcnt(30)
	v_and_b32_e32 v197, 0xffff0000, v2
	v_and_b32_e32 v195, 0xffff0000, v3
	v_add_f32_e32 v134, v134, v135
	v_lshlrev_b32_e32 v196, 16, v2
	v_lshlrev_b32_e32 v194, 16, v3
	v_mul_f32_e32 v135, v197, v197
	v_mul_f32_e32 v136, v195, v195
	v_fmac_f32_e32 v135, v196, v196
	v_fmac_f32_e32 v136, v194, v194
	v_add_f32_e32 v135, v135, v136
	s_waitcnt vmcnt(29)
	v_and_b32_e32 v193, 0xffff0000, v4
	v_and_b32_e32 v191, 0xffff0000, v5
	v_add_f32_e32 v134, v134, v135
	v_lshlrev_b32_e32 v192, 16, v4
	v_lshlrev_b32_e32 v190, 16, v5
	v_mul_f32_e32 v135, v193, v193
	v_mul_f32_e32 v136, v191, v191
	v_fmac_f32_e32 v135, v192, v192
	v_fmac_f32_e32 v136, v190, v190
	v_add_f32_e32 v135, v135, v136
	s_waitcnt vmcnt(28)
	v_and_b32_e32 v189, 0xffff0000, v6
	v_and_b32_e32 v187, 0xffff0000, v7
	v_add_f32_e32 v134, v135, v134
	v_lshlrev_b32_e32 v188, 16, v6
	v_lshlrev_b32_e32 v186, 16, v7
	v_mul_f32_e32 v135, v189, v189
	v_mul_f32_e32 v136, v187, v187
	v_fmac_f32_e32 v135, v188, v188
	v_fmac_f32_e32 v136, v186, v186
	v_add_f32_e32 v135, v135, v136
	s_waitcnt vmcnt(27)
	v_and_b32_e32 v185, 0xffff0000, v8
	v_and_b32_e32 v183, 0xffff0000, v9
	v_add_f32_e32 v134, v135, v134
	v_lshlrev_b32_e32 v184, 16, v8
	v_lshlrev_b32_e32 v182, 16, v9
	v_mul_f32_e32 v135, v185, v185
	v_mul_f32_e32 v136, v183, v183
	v_fmac_f32_e32 v135, v184, v184
	v_fmac_f32_e32 v136, v182, v182
	v_add_f32_e32 v135, v135, v136
	s_waitcnt vmcnt(26)
	v_and_b32_e32 v181, 0xffff0000, v10
	v_and_b32_e32 v179, 0xffff0000, v11
	v_add_f32_e32 v134, v135, v134
	v_lshlrev_b32_e32 v180, 16, v10
	v_lshlrev_b32_e32 v178, 16, v11
	v_mul_f32_e32 v135, v181, v181
	v_mul_f32_e32 v136, v179, v179
	v_fmac_f32_e32 v135, v180, v180
	v_fmac_f32_e32 v136, v178, v178
	v_add_f32_e32 v135, v135, v136
	s_waitcnt vmcnt(25)
	v_and_b32_e32 v177, 0xffff0000, v12
	v_and_b32_e32 v175, 0xffff0000, v13
	v_add_f32_e32 v134, v135, v134
	v_lshlrev_b32_e32 v176, 16, v12
	v_lshlrev_b32_e32 v174, 16, v13
	v_mul_f32_e32 v135, v177, v177
	v_mul_f32_e32 v136, v175, v175
	v_fmac_f32_e32 v135, v176, v176
	v_fmac_f32_e32 v136, v174, v174
	v_add_f32_e32 v135, v135, v136
	s_waitcnt vmcnt(24)
	v_and_b32_e32 v171, 0xffff0000, v14
	v_and_b32_e32 v169, 0xffff0000, v15
	v_add_f32_e32 v134, v135, v134
	v_lshlrev_b32_e32 v170, 16, v14
	v_lshlrev_b32_e32 v168, 16, v15
	v_mul_f32_e32 v135, v171, v171
	v_mul_f32_e32 v136, v169, v169
	v_fmac_f32_e32 v135, v170, v170
	v_fmac_f32_e32 v136, v168, v168
	v_add_f32_e32 v135, v135, v136
	s_waitcnt vmcnt(23)
	v_and_b32_e32 v167, 0xffff0000, v16
	v_and_b32_e32 v165, 0xffff0000, v17
	v_add_f32_e32 v134, v135, v134
	v_lshlrev_b32_e32 v166, 16, v16
	v_lshlrev_b32_e32 v164, 16, v17
	v_mul_f32_e32 v135, v167, v167
	v_mul_f32_e32 v136, v165, v165
	v_fmac_f32_e32 v135, v166, v166
	v_fmac_f32_e32 v136, v164, v164
	v_add_f32_e32 v135, v135, v136
	s_waitcnt vmcnt(22)
	v_and_b32_e32 v161, 0xffff0000, v18
	v_and_b32_e32 v163, 0xffff0000, v19
	v_add_f32_e32 v134, v135, v134
	v_lshlrev_b32_e32 v160, 16, v18
	v_lshlrev_b32_e32 v162, 16, v19
	v_mul_f32_e32 v135, v161, v161
	v_mul_f32_e32 v136, v163, v163
	v_fmac_f32_e32 v135, v160, v160
	v_fmac_f32_e32 v136, v162, v162
	v_add_f32_e32 v135, v135, v136
	s_waitcnt vmcnt(21)
	v_and_b32_e32 v157, 0xffff0000, v20
	v_and_b32_e32 v159, 0xffff0000, v21
	v_add_f32_e32 v134, v135, v134
	v_lshlrev_b32_e32 v156, 16, v20
	v_lshlrev_b32_e32 v158, 16, v21
	v_mul_f32_e32 v135, v157, v157
	v_mul_f32_e32 v136, v159, v159
	v_fmac_f32_e32 v135, v156, v156
	v_fmac_f32_e32 v136, v158, v158
	v_add_f32_e32 v135, v135, v136
	s_waitcnt vmcnt(20)
	v_and_b32_e32 v153, 0xffff0000, v22
	v_and_b32_e32 v155, 0xffff0000, v23
	v_add_f32_e32 v134, v135, v134
	v_lshlrev_b32_e32 v152, 16, v22
	v_lshlrev_b32_e32 v154, 16, v23
	v_mul_f32_e32 v135, v153, v153
	v_mul_f32_e32 v136, v155, v155
	v_fmac_f32_e32 v135, v152, v152
	v_fmac_f32_e32 v136, v154, v154
	v_add_f32_e32 v135, v135, v136
	s_waitcnt vmcnt(19)
	v_and_b32_e32 v147, 0xffff0000, v24
	v_and_b32_e32 v149, 0xffff0000, v25
	v_add_f32_e32 v134, v135, v134
	v_lshlrev_b32_e32 v146, 16, v24
	v_lshlrev_b32_e32 v148, 16, v25
	v_mul_f32_e32 v135, v147, v147
	v_mul_f32_e32 v136, v149, v149
	v_fmac_f32_e32 v135, v146, v146
	v_fmac_f32_e32 v136, v148, v148
	v_add_f32_e32 v135, v135, v136
	s_waitcnt vmcnt(18)
	v_and_b32_e32 v143, 0xffff0000, v26
	v_and_b32_e32 v145, 0xffff0000, v27
	v_add_f32_e32 v134, v135, v134
	v_lshlrev_b32_e32 v142, 16, v26
	v_lshlrev_b32_e32 v144, 16, v27
	v_mul_f32_e32 v135, v143, v143
	v_mul_f32_e32 v136, v145, v145
	v_fmac_f32_e32 v135, v142, v142
	v_fmac_f32_e32 v136, v144, v144
	v_add_f32_e32 v135, v135, v136
	s_waitcnt vmcnt(17)
	v_and_b32_e32 v139, 0xffff0000, v28
	v_and_b32_e32 v141, 0xffff0000, v29
	v_add_f32_e32 v134, v135, v134
	v_lshlrev_b32_e32 v138, 16, v28
	v_lshlrev_b32_e32 v140, 16, v29
	v_mul_f32_e32 v135, v139, v139
	v_mul_f32_e32 v136, v141, v141
	v_fmac_f32_e32 v135, v138, v138
	v_fmac_f32_e32 v136, v140, v140
	v_add_f32_e32 v135, v135, v136
	v_add_f32_e32 v150, v135, v134
	s_waitcnt vmcnt(16)
	v_and_b32_e32 v135, 0xffff0000, v30
	v_and_b32_e32 v137, 0xffff0000, v31
	v_lshlrev_b32_e32 v134, 16, v30
	v_lshlrev_b32_e32 v136, 16, v31
	v_mul_f32_e32 v172, v135, v135
	v_mul_f32_e32 v173, v137, v137
	v_fmac_f32_e32 v172, v134, v134
	v_fmac_f32_e32 v173, v136, v136
	v_add_f32_e32 v172, v172, v173
	v_add_f32_e32 v150, v172, v150
	ds_bpermute_b32 v172, v204, v150
	s_ashr_i32 s25, s24, 31
	s_waitcnt vmcnt(15)
	v_lshlrev_b32_e32 v214, 16, v38
	v_and_b32_e32 v215, 0xffff0000, v38
	s_waitcnt lgkmcnt(0)
	v_add_f32_e32 v150, v150, v172
	ds_bpermute_b32 v172, v205, v150
	v_lshlrev_b32_e32 v216, 16, v39
	v_and_b32_e32 v217, 0xffff0000, v39
	s_waitcnt lgkmcnt(0)
	v_add_f32_e32 v150, v150, v172
	ds_bpermute_b32 v172, v206, v150
	s_waitcnt lgkmcnt(0)
	v_add_f32_e32 v150, v150, v172
	ds_bpermute_b32 v172, v207, v150
	s_waitcnt lgkmcnt(0)
	v_add_f32_e32 v150, v150, v172
	ds_bpermute_b32 v172, v208, v150
	s_waitcnt lgkmcnt(0)
	v_add_f32_e32 v150, v150, v172
	ds_bpermute_b32 v172, v209, v150
	s_waitcnt lgkmcnt(0)
	v_add_f32_e32 v150, v150, v172
	v_fmamk_f32 v150, v150, 0x39800000, v198
	v_mul_f32_e32 v172, 0x4f800000, v150
	v_cmp_gt_f32_e32 vcc, s8, v150
	s_nop 1
	v_cndmask_b32_e32 v150, v150, v172, vcc
	v_sqrt_f32_e32 v172, v150
	s_nop 0
	v_add_u32_e32 v173, -1, v172
	v_fma_f32 v200, -v173, v172, v150
	v_cmp_ge_f32_e64 s[0:1], 0, v200
	v_add_u32_e32 v200, 1, v172
	s_nop 0
	v_cndmask_b32_e64 v173, v172, v173, s[0:1]
	v_fma_f32 v172, -v200, v172, v150
	v_cmp_lt_f32_e64 s[0:1], 0, v172
	s_nop 1
	v_cndmask_b32_e64 v172, v173, v200, s[0:1]
	v_mul_f32_e32 v173, 0x37800000, v172
	v_cndmask_b32_e32 v172, v172, v173, vcc
	v_cmp_class_f32_e32 vcc, v150, v199
	s_nop 1
	v_cndmask_b32_e32 v150, v172, v150, vcc
	v_div_scale_f32 v172, s[0:1], v150, v150, 1.0
	v_rcp_f32_e32 v173, v172
	s_lshl_b64 s[0:1], s[24:25], 14
	v_fma_f32 v200, -v172, v173, 1.0
	v_fmac_f32_e32 v173, v200, v173
	v_div_scale_f32 v200, vcc, 1.0, v150, 1.0
	v_mul_f32_e32 v201, v200, v173
	v_fma_f32 v202, -v172, v201, v200
	v_fmac_f32_e32 v201, v202, v173
	v_fma_f32 v172, -v172, v201, v200
	v_div_fmas_f32 v172, v172, v173, v201
	v_div_fixup_f32 v150, v172, v150, 1.0
	ds_read_b128 v[200:203], v151
	v_mul_f32_e32 v150, 0.5, v150
	v_pk_mul_f32 v[218:219], v[150:151], v[210:211] op_sel_hi:[0,1]
	v_pk_mul_f32 v[220:221], v[150:151], v[212:213] op_sel_hi:[0,1]
	ds_read_b128 v[210:213], v151 offset:1024
	v_lshl_add_u64 v[172:173], v[36:37], 0, s[0:1]
	s_waitcnt lgkmcnt(1)
	v_pk_fma_f32 v[202:203], v[202:203], v[220:221], v[216:217]
	v_pk_fma_f32 v[200:201], v[200:201], v[218:219], v[214:215]
	global_store_dwordx4 v[172:173], v[200:203], off nt
	v_pk_mul_f32 v[214:215], v[150:151], v[196:197] op_sel_hi:[0,1]
	v_pk_mul_f32 v[194:195], v[150:151], v[194:195] op_sel_hi:[0,1]
	s_waitcnt vmcnt(15)
	v_lshlrev_b32_e32 v200, 16, v40
	v_and_b32_e32 v201, 0xffff0000, v40
	v_lshlrev_b32_e32 v202, 16, v41
	v_and_b32_e32 v203, 0xffff0000, v41
	s_waitcnt lgkmcnt(0)
	v_pk_fma_f32 v[196:197], v[212:213], v[194:195], v[202:203]
	v_pk_fma_f32 v[194:195], v[210:211], v[214:215], v[200:201]
	global_store_dwordx4 v[172:173], v[194:197], off offset:1024 nt
	ds_read_b128 v[194:197], v151 offset:2048
	v_pk_mul_f32 v[210:211], v[150:151], v[192:193] op_sel_hi:[0,1]
	v_pk_mul_f32 v[212:213], v[150:151], v[190:191] op_sel_hi:[0,1]
	ds_read_b128 v[190:193], v151 offset:3072
	s_waitcnt vmcnt(15)
	v_lshlrev_b32_e32 v200, 16, v42
	v_and_b32_e32 v201, 0xffff0000, v42
	v_lshlrev_b32_e32 v202, 16, v43
	v_and_b32_e32 v203, 0xffff0000, v43
	s_waitcnt lgkmcnt(1)
	v_pk_fma_f32 v[196:197], v[196:197], v[212:213], v[202:203]
	v_pk_fma_f32 v[194:195], v[194:195], v[210:211], v[200:201]
	global_store_dwordx4 v[172:173], v[194:197], off offset:2048 nt
	v_pk_mul_f32 v[200:201], v[150:151], v[188:189] op_sel_hi:[0,1]
	v_pk_mul_f32 v[186:187], v[150:151], v[186:187] op_sel_hi:[0,1]
	s_waitcnt vmcnt(15)
	v_lshlrev_b32_e32 v194, 16, v44
	v_and_b32_e32 v195, 0xffff0000, v44
	v_lshlrev_b32_e32 v196, 16, v45
	v_and_b32_e32 v197, 0xffff0000, v45
	s_waitcnt lgkmcnt(0)
	v_pk_fma_f32 v[188:189], v[192:193], v[186:187], v[196:197]
	v_pk_fma_f32 v[186:187], v[190:191], v[200:201], v[194:195]
	global_store_dwordx4 v[172:173], v[186:189], off offset:3072 nt
	ds_read_b128 v[186:189], v151 offset:4096
	s_waitcnt vmcnt(15)
	v_lshlrev_b32_e32 v190, 16, v46
	v_and_b32_e32 v191, 0xffff0000, v46
	v_pk_mul_f32 v[194:195], v[150:151], v[184:185] op_sel_hi:[0,1]
	v_pk_mul_f32 v[196:197], v[150:151], v[182:183] op_sel_hi:[0,1]
	ds_read_b128 v[182:185], v151 offset:5120
	s_waitcnt lgkmcnt(1)
	v_pk_fma_f32 v[186:187], v[186:187], v[194:195], v[190:191]
	v_add_co_u32_e32 v190, vcc, s6, v172
	v_lshlrev_b32_e32 v192, 16, v47
	v_and_b32_e32 v193, 0xffff0000, v47
	v_addc_co_u32_e32 v191, vcc, 0, v173, vcc
	v_pk_fma_f32 v[188:189], v[188:189], v[196:197], v[192:193]
	v_add_co_u32_e32 v192, vcc, s9, v172
	v_pk_mul_f32 v[194:195], v[150:151], v[180:181] op_sel_hi:[0,1]
	s_nop 0
	v_addc_co_u32_e32 v193, vcc, 0, v173, vcc
	global_store_dwordx4 v[192:193], v[186:189], off offset:-4096 nt
	v_pk_mul_f32 v[178:179], v[150:151], v[178:179] op_sel_hi:[0,1]
	v_pk_mul_f32 v[168:169], v[150:151], v[168:169] op_sel_hi:[0,1]
	s_waitcnt vmcnt(15)
	v_lshlrev_b32_e32 v186, 16, v48
	v_and_b32_e32 v187, 0xffff0000, v48
	v_lshlrev_b32_e32 v188, 16, v49
	v_and_b32_e32 v189, 0xffff0000, v49
	s_waitcnt lgkmcnt(0)
	v_pk_fma_f32 v[180:181], v[178:179], v[184:185], v[188:189]
	v_pk_fma_f32 v[178:179], v[194:195], v[182:183], v[186:187]
	global_store_dwordx4 v[190:191], v[178:181], off offset:1024 nt
	ds_read_b128 v[178:181], v151 offset:6144
	v_pk_mul_f32 v[186:187], v[150:151], v[176:177] op_sel_hi:[0,1]
	v_pk_mul_f32 v[188:189], v[150:151], v[174:175] op_sel_hi:[0,1]
	ds_read_b128 v[174:177], v151 offset:7168
	s_waitcnt vmcnt(15)
	v_lshlrev_b32_e32 v182, 16, v50
	v_and_b32_e32 v183, 0xffff0000, v50
	v_lshlrev_b32_e32 v184, 16, v51
	v_and_b32_e32 v185, 0xffff0000, v51
	s_waitcnt lgkmcnt(1)
	v_pk_fma_f32 v[180:181], v[188:189], v[180:181], v[184:185]
	v_pk_fma_f32 v[178:179], v[186:187], v[178:179], v[182:183]
	global_store_dwordx4 v[190:191], v[178:181], off offset:2048 nt
	v_pk_mul_f32 v[182:183], v[150:151], v[170:171] op_sel_hi:[0,1]
	v_pk_mul_f32 v[162:163], v[150:151], v[162:163] op_sel_hi:[0,1]
	s_waitcnt vmcnt(15)
	v_lshlrev_b32_e32 v178, 16, v52
	v_and_b32_e32 v179, 0xffff0000, v52
	v_lshlrev_b32_e32 v180, 16, v53
	v_and_b32_e32 v181, 0xffff0000, v53
	s_waitcnt lgkmcnt(0)
	v_pk_fma_f32 v[170:171], v[168:169], v[176:177], v[180:181]
	v_pk_fma_f32 v[168:169], v[182:183], v[174:175], v[178:179]
	global_store_dwordx4 v[190:191], v[168:171], off offset:3072 nt
	ds_read_b128 v[168:171], v151 offset:8192
	v_pk_mul_f32 v[178:179], v[150:151], v[166:167] op_sel_hi:[0,1]
	v_pk_mul_f32 v[180:181], v[150:151], v[164:165] op_sel_hi:[0,1]
	ds_read_b128 v[164:167], v151 offset:9216
	s_waitcnt vmcnt(15)
	v_lshlrev_b32_e32 v174, 16, v54
	v_and_b32_e32 v175, 0xffff0000, v54
	v_lshlrev_b32_e32 v176, 16, v55
	v_and_b32_e32 v177, 0xffff0000, v55
	s_waitcnt lgkmcnt(1)
	v_pk_fma_f32 v[170:171], v[180:181], v[170:171], v[176:177]
	v_pk_fma_f32 v[168:169], v[178:179], v[168:169], v[174:175]
	global_store_dwordx4 v[192:193], v[168:171], off nt
	v_pk_mul_f32 v[160:161], v[150:151], v[160:161] op_sel_hi:[0,1]
	v_pk_mul_f32 v[154:155], v[150:151], v[154:155] op_sel_hi:[0,1]
	s_waitcnt vmcnt(15)
	v_lshlrev_b32_e32 v168, 16, v56
	v_and_b32_e32 v169, 0xffff0000, v56
	v_lshlrev_b32_e32 v170, 16, v57
	v_and_b32_e32 v171, 0xffff0000, v57
	s_waitcnt lgkmcnt(0)
	v_pk_fma_f32 v[160:161], v[160:161], v[164:165], v[168:169]
	v_pk_fma_f32 v[162:163], v[162:163], v[166:167], v[170:171]
	global_store_dwordx4 v[192:193], v[160:163], off offset:1024 nt
	ds_read_b128 v[160:163], v151 offset:10240
	v_pk_mul_f32 v[168:169], v[150:151], v[158:159] op_sel_hi:[0,1]
	v_pk_mul_f32 v[170:171], v[150:151], v[156:157] op_sel_hi:[0,1]
	ds_read_b128 v[156:159], v151 offset:11264
	s_waitcnt vmcnt(15)
	v_lshlrev_b32_e32 v164, 16, v58
	v_and_b32_e32 v165, 0xffff0000, v58
	v_lshlrev_b32_e32 v166, 16, v59
	v_and_b32_e32 v167, 0xffff0000, v59
	s_waitcnt lgkmcnt(1)
	v_pk_fma_f32 v[160:161], v[170:171], v[160:161], v[164:165]
	v_pk_fma_f32 v[162:163], v[168:169], v[162:163], v[166:167]
	global_store_dwordx4 v[192:193], v[160:163], off offset:2048 nt
	v_pk_mul_f32 v[152:153], v[150:151], v[152:153] op_sel_hi:[0,1]
	v_pk_mul_f32 v[144:145], v[150:151], v[144:145] op_sel_hi:[0,1]
	s_waitcnt vmcnt(15)
	v_lshlrev_b32_e32 v160, 16, v60
	v_and_b32_e32 v161, 0xffff0000, v60
	v_lshlrev_b32_e32 v162, 16, v61
	v_and_b32_e32 v163, 0xffff0000, v61
	s_waitcnt lgkmcnt(0)
	v_pk_fma_f32 v[152:153], v[152:153], v[156:157], v[160:161]
	v_pk_fma_f32 v[154:155], v[154:155], v[158:159], v[162:163]
	global_store_dwordx4 v[192:193], v[152:155], off offset:3072 nt
	ds_read_b128 v[152:155], v151 offset:12288
	v_pk_mul_f32 v[160:161], v[150:151], v[148:149] op_sel_hi:[0,1]
	v_pk_mul_f32 v[162:163], v[150:151], v[146:147] op_sel_hi:[0,1]
	ds_read_b128 v[146:149], v151 offset:13312
	s_waitcnt vmcnt(15)
	v_lshlrev_b32_e32 v156, 16, v62
	v_and_b32_e32 v157, 0xffff0000, v62
	v_lshlrev_b32_e32 v158, 16, v63
	v_and_b32_e32 v159, 0xffff0000, v63
	s_waitcnt lgkmcnt(1)
	v_pk_fma_f32 v[152:153], v[162:163], v[152:153], v[156:157]
	v_add_co_u32_e32 v156, vcc, s10, v172
	v_pk_fma_f32 v[154:155], v[160:161], v[154:155], v[158:159]
	s_nop 0
	v_addc_co_u32_e32 v157, vcc, 0, v173, vcc
	global_store_dwordx4 v[156:157], v[152:155], off nt
	v_pk_mul_f32 v[142:143], v[150:151], v[142:143] op_sel_hi:[0,1]
	v_pk_mul_f32 v[136:137], v[150:151], v[136:137] op_sel_hi:[0,1]
	s_waitcnt vmcnt(15)
	v_lshlrev_b32_e32 v152, 16, v64
	v_and_b32_e32 v153, 0xffff0000, v64
	v_lshlrev_b32_e32 v154, 16, v65
	v_and_b32_e32 v155, 0xffff0000, v65
	s_waitcnt lgkmcnt(0)
	v_pk_fma_f32 v[142:143], v[142:143], v[146:147], v[152:153]
	v_pk_fma_f32 v[144:145], v[144:145], v[148:149], v[154:155]
	global_store_dwordx4 v[156:157], v[142:145], off offset:1024 nt
	ds_read_b128 v[142:145], v151 offset:14336
	v_pk_mul_f32 v[152:153], v[150:151], v[140:141] op_sel_hi:[0,1]
	v_pk_mul_f32 v[154:155], v[150:151], v[138:139] op_sel_hi:[0,1]
	ds_read_b128 v[138:141], v151 offset:15360
	s_waitcnt vmcnt(15)
	v_lshlrev_b32_e32 v146, 16, v66
	v_and_b32_e32 v147, 0xffff0000, v66
	v_lshlrev_b32_e32 v148, 16, v67
	v_and_b32_e32 v149, 0xffff0000, v67
	s_waitcnt lgkmcnt(1)
	v_pk_fma_f32 v[142:143], v[154:155], v[142:143], v[146:147]
	v_pk_fma_f32 v[144:145], v[152:153], v[144:145], v[148:149]
	global_store_dwordx4 v[156:157], v[142:145], off offset:2048 nt
	v_pk_mul_f32 v[134:135], v[150:151], v[134:135] op_sel_hi:[0,1]
	s_mov_b64 s[0:1], -1
	s_waitcnt vmcnt(15)
	v_lshlrev_b32_e32 v142, 16, v68
	v_and_b32_e32 v143, 0xffff0000, v68
	v_lshlrev_b32_e32 v144, 16, v69
	v_and_b32_e32 v145, 0xffff0000, v69
	s_waitcnt lgkmcnt(0)
	v_pk_fma_f32 v[134:135], v[134:135], v[138:139], v[142:143]
	v_pk_fma_f32 v[136:137], v[136:137], v[140:141], v[144:145]
	s_andn2_b64 vcc, exec, s[4:5]
	v_readfirstlane_b32 s4, v0
	global_store_dwordx4 v[156:157], v[134:137], off offset:3072 nt
	s_cbranch_vccnz .LBB0_2060
	s_add_i32 s0, s7, s24
	s_cmpk_gt_i32 s0, 0x3fff
	s_cbranch_scc1 .LBB0_2059
	s_ashr_i32 s1, s0, 31
	s_lshl_b64 s[0:1], s[0:1], 13
	v_lshl_add_u64 v[16:17], v[32:33], 0, s[0:1]
	v_add_co_u32_e32 v38, vcc, 0x1000, v16
	v_lshl_add_u64 v[54:55], v[34:35], 0, s[0:1]
	s_nop 0
	v_addc_co_u32_e32 v39, vcc, 0, v17, vcc
	v_add_co_u32_e32 v68, vcc, s6, v54
	global_load_dwordx2 v[0:1], v[16:17], off nt
	global_load_dwordx2 v[2:3], v[16:17], off offset:512 nt
	global_load_dwordx2 v[4:5], v[16:17], off offset:1024 nt
	global_load_dwordx2 v[6:7], v[16:17], off offset:1536 nt
	global_load_dwordx2 v[8:9], v[16:17], off offset:2048 nt
	global_load_dwordx2 v[10:11], v[16:17], off offset:2560 nt
	global_load_dwordx2 v[12:13], v[16:17], off offset:3072 nt
	global_load_dwordx2 v[14:15], v[16:17], off offset:3584 nt
	v_addc_co_u32_e32 v69, vcc, 0, v55, vcc
	global_load_dwordx2 v[16:17], v[38:39], off nt
	global_load_dwordx2 v[18:19], v[38:39], off offset:512 nt
	global_load_dwordx2 v[20:21], v[38:39], off offset:1024 nt
	global_load_dwordx2 v[22:23], v[38:39], off offset:1536 nt
	global_load_dwordx2 v[24:25], v[38:39], off offset:2048 nt
	global_load_dwordx2 v[26:27], v[38:39], off offset:2560 nt
	global_load_dwordx2 v[28:29], v[38:39], off offset:3072 nt
	global_load_dwordx2 v[30:31], v[38:39], off offset:3584 nt
	s_nop 0
	global_load_dwordx2 v[38:39], v[54:55], off nt
	global_load_dwordx2 v[40:41], v[54:55], off offset:512 nt
	global_load_dwordx2 v[42:43], v[54:55], off offset:1024 nt
	global_load_dwordx2 v[44:45], v[54:55], off offset:1536 nt
	global_load_dwordx2 v[46:47], v[54:55], off offset:2048 nt
	global_load_dwordx2 v[48:49], v[54:55], off offset:2560 nt
	global_load_dwordx2 v[50:51], v[54:55], off offset:3072 nt
	global_load_dwordx2 v[52:53], v[54:55], off offset:3584 nt
	s_nop 0
	global_load_dwordx2 v[54:55], v[68:69], off nt
	global_load_dwordx2 v[56:57], v[68:69], off offset:512 nt
	global_load_dwordx2 v[58:59], v[68:69], off offset:1024 nt
	global_load_dwordx2 v[60:61], v[68:69], off offset:1536 nt
	global_load_dwordx2 v[62:63], v[68:69], off offset:2048 nt
	global_load_dwordx2 v[64:65], v[68:69], off offset:2560 nt
	global_load_dwordx2 v[66:67], v[68:69], off offset:3072 nt
	s_nop 0
	global_load_dwordx2 v[68:69], v[68:69], off offset:3584 nt
	s_branch .LBB0_2059
